# attention: coalesced K via LDS staging, finalize de-serialised, interleaved pass deal; GEMM vmcnt hoist
# speedup vs baseline: 1.0149x; 1.0149x over previous
.LBB0_246:
	s_and_b64 vcc, exec, s[48:49]
	s_cbranch_vccz .LBB0_250
	s_movk_i32 s14, 0x100
	s_movk_i32 s12, 0x100
	s_mov_b32 s13, 1
	s_movk_i32 s18, 0x208
	s_movk_i32 s15, 0x208
	s_cmp_lt_i32 s4, 16
	s_cbranch_scc1 .LBB0_249
	s_lshr_b32 s0, s4, 5
	s_add_i32 s1, s4, -16
	s_mul_i32 s2, s0, 0x1a0
	s_add_i32 s3, s2, 0xd0
	s_add_i32 s2, s2, 0xffffff30
	s_max_i32 s2, s2, 0
	s_mul_hi_u32 s2, s2, 0xaaaaaaab
	s_lshr_b32 s2, s2, 2
	s_mul_hi_u32 s3, s3, 0xaaaaaaab
	s_lshr_b32 s3, s3, 2
	s_cmp_eq_u32 s0, 0
	s_cselect_b32 s13, 16, 32
	s_lshl_b32 s6, s0, 5
	s_add_i32 s6, s6, -16
	s_max_i32 s6, s6, 0
	s_sub_i32 s7, s1, s6
	s_add_i32 s18, s2, s7
	s_mov_b32 s15, s3
	s_lshl_b32 s7, s13, 1
	s_add_i32 s2, s18, s7
	s_cmp_ge_i32 s2, s15
	s_cbranch_scc0 .LBB0_249
	s_lshl_b32 s6, s6, 1
	s_add_i32 s6, s6, s1
	s_add_i32 s6, s6, s7
	s_sub_i32 s0, s6, s3
	s_lshl_b32 s0, s0, 8
	s_add_i32 s1, s0, 0x100
	s_mul_hi_i32 s0, s0, 0x51eb851f
	s_lshr_b32 s2, s0, 31
	s_ashr_i32 s0, s0, 6
	s_add_i32 s12, s0, s2
	s_mul_hi_i32 s0, s1, 0x51eb851f
	s_lshr_b32 s1, s0, 31
	s_ashr_i32 s0, s0, 6
	s_add_i32 s14, s0, s1
.LBB0_249:
	s_cmp_ge_i32 s18, s15
	s_cbranch_scc0 .LBB0_251
	s_branch .LBB0_310

.LBB0_262:
	s_cmpk_lt_i32 s18, 0x200
	s_mov_b64 s[0:1], -1
	s_cbranch_scc0 .LBB0_285
	s_mov_b64 s[8:9], s[36:37]
	v_mov_b32_e32 v12, v224
	s_load_dwordx2 s[2:3], s[8:9], 0xa8
	s_and_b32 s6, s22, 0xffffe000
	s_bfe_u32 s7, s18, 0x70001
	v_ashrrev_i32_e32 v0, 6, v12
	s_movk_i32 s4, 0x2400
	s_waitcnt lgkmcnt(0)
	s_add_u32 s0, s2, 0x6000000
	s_addc_u32 s1, s3, 0
	v_mul_lo_u32 v4, v0, s4
	s_lshl_b32 s4, s18, 5
	v_and_b32_e32 v252, 31, v12
	v_mul_lo_u32 v0, v0, s61
	s_and_b32 s11, s4, 0xffffe000
	s_lshl_b32 s5, s7, 6
	s_and_b32 s10, s4, 32
	v_add_u32_e32 v246, s19, v0
	s_or_b32 s5, s5, s11
	v_or_b32_e32 v0, s10, v252
	s_waitcnt vmcnt(10)
	v_or_b32_e32 v162, s5, v0
	v_mov_b64_e32 v[0:1], s[0:1]
	s_movk_i32 s4, 0x1c00
	v_mad_i64_i32 v[0:1], s[4:5], v162, s4, v[0:1]
	s_sub_i32 s4, 8, s7
	s_cmp_lt_u32 s7, 8
	s_cselect_b32 s29, s4, 0
	s_add_i32 s4, s29, s7
	s_lshl_b32 s7, s4, 6
	v_and_b32_e32 v164, 0xffffffc0, v12
	s_add_i32 s4, s11, s7
	v_ashrrev_i32_e32 v165, 31, v164
	s_addk_i32 s4, 0xfe00
	v_bfe_u32 v13, v12, 5, 1
	v_lshlrev_b64 v[2:3], 1, v[164:165]
	s_mul_hi_i32 s5, s4, 0x1c00
	s_mulk_i32 s4, 0x1c00
	v_lshl_add_u64 v[0:1], v[0:1], 0, v[2:3]
	v_lshlrev_b32_e32 v112, 4, v13
	s_add_u32 s4, s0, s4
	v_lshl_add_u64 v[0:1], v[0:1], 0, v[112:113]
	v_add_u32_e32 v15, s24, v4
	s_addc_u32 s5, s1, s5
	v_mul_u32_u24_e32 v4, 0xe00, v252
	global_load_dwordx4 v[64:67], v[0:1], off
	global_load_dwordx4 v[68:71], v[0:1], off offset:32
	global_load_dwordx4 v[72:75], v[0:1], off offset:64
	global_load_dwordx4 v[76:79], v[0:1], off offset:96
	v_lshl_add_u64 v[0:1], s[4:5], 0, v[2:3]
	v_lshlrev_b32_e32 v4, 1, v4
	v_mov_b32_e32 v5, v113
	v_lshl_add_u64 v[6:7], v[0:1], 0, v[4:5]
	v_lshl_add_u64 v[6:7], v[6:7], 0, v[112:113]
	ds_read_b32 v166, v246 offset:1276
	v_bfe_u32 v216, v12, 3, 3
	v_and_b32_e32 v217, 7, v12
	v_lshlrev_b32_e32 v213, 1, v164
	v_mad_u32_u24 v213, v216, v238, v213
	v_lshl_add_u32 v213, v217, 4, v213
	v_add_u32_e32 v213, 0x400, v213
	v_mul_u32_u24_e32 v214, 0x48, v164
	v_add_u32_e32 v214, 0x15000, v214
	v_add_u32_e32 v214, s24, v214
	v_mul_u32_u24_e32 v215, 0x90, v252
	v_lshl_add_u32 v215, v13, 4, v215
	v_add_u32_e32 v215, v215, v214
	v_mul_u32_u24_e32 v218, 0x90, v216
	v_lshl_add_u32 v218, v217, 4, v218
	v_add_u32_e32 v214, v214, v218
	s_mov_b64 s[38:39], s[4:5]
	global_load_dwordx4 v[80:83], v213, s[38:39]
	s_add_u32 s38, s38, 0xe000
	s_addc_u32 s39, s39, 0
	global_load_dwordx4 v[84:87], v213, s[38:39]
	s_add_u32 s38, s38, 0xe000
	s_addc_u32 s39, s39, 0
	global_load_dwordx4 v[88:91], v213, s[38:39]
	s_add_u32 s38, s38, 0xe000
	s_addc_u32 s39, s39, 0
	global_load_dwordx4 v[92:95], v213, s[38:39]
	s_add_u32 s38, s38, 0xe000
	s_addc_u32 s39, s39, 0
	v_bfe_u32 v16, v12, 3, 3
	v_lshlrev_b32_e32 v6, 4, v12
	v_and_b32_e32 v6, 0x70, v6
	v_mov_b32_e32 v7, v113
	v_mul_u32_u24_e32 v34, 0xe00, v16
	v_lshl_add_u64 v[0:1], v[0:1], 0, v[6:7]
	v_lshlrev_b32_e32 v8, 1, v34
	v_mov_b32_e32 v9, v113
	v_lshl_add_u64 v[8:9], v[0:1], 0, v[8:9]
	s_mov_b32 s4, 0xe000
	v_add_co_u32_e32 v10, vcc, s4, v8
	s_mov_b32 s4, 0x1c000
	s_nop 0
	v_addc_co_u32_e32 v11, vcc, 0, v9, vcc
	global_load_dwordx4 v[96:99], v[8:9], off offset:2048
	global_load_dwordx4 v[100:103], v[10:11], off offset:2048
	v_add_co_u32_e32 v10, vcc, s4, v8
	s_mov_b32 s4, 0x2a000
	s_nop 0
	v_addc_co_u32_e32 v11, vcc, 0, v9, vcc
	v_add_co_u32_e32 v8, vcc, s4, v8
	s_movk_i32 s4, 0xe00
	s_nop 0
	v_addc_co_u32_e32 v9, vcc, 0, v9, vcc
	global_load_dwordx4 v[104:107], v[10:11], off offset:2048
	global_load_dwordx4 v[108:111], v[8:9], off offset:2048
	v_mov_b32_e32 v8, 0x1c000
	v_mad_u32_u24 v36, v16, s4, v8
	v_mov_b32_e32 v10, 0x23000
	v_lshlrev_b32_e32 v8, 1, v36
	v_mov_b32_e32 v9, v113
	v_mad_u32_u24 v38, v16, s4, v10
	v_lshl_add_u64 v[8:9], v[0:1], 0, v[8:9]
	v_lshlrev_b32_e32 v10, 1, v38
	v_mov_b32_e32 v11, v113
	v_lshl_add_u64 v[10:11], v[0:1], 0, v[10:11]
	global_load_dwordx4 v[114:117], v[8:9], off offset:2048
	global_load_dwordx4 v[118:121], v[10:11], off offset:2048
	v_mov_b32_e32 v8, 0x2a000
	v_mad_u32_u24 v40, v16, s4, v8
	v_mov_b32_e32 v10, 0x31000
	v_lshlrev_b32_e32 v8, 1, v40
	v_mov_b32_e32 v9, v113
	v_mad_u32_u24 v42, v16, s4, v10
	v_lshl_add_u64 v[8:9], v[0:1], 0, v[8:9]
	v_lshlrev_b32_e32 v10, 1, v42
	v_mov_b32_e32 v11, v113
	v_lshl_add_u64 v[0:1], v[0:1], 0, v[10:11]
	global_load_dwordx4 v[122:125], v[8:9], off offset:2048
	global_load_dwordx4 v[126:129], v[0:1], off offset:2048
	global_load_dwordx4 v[146:149], v213, s[38:39]
	s_add_u32 s38, s38, 0xe000
	s_addc_u32 s39, s39, 0
	global_load_dwordx4 v[150:153], v213, s[38:39]
	s_add_u32 s38, s38, 0xe000
	s_addc_u32 s39, s39, 0
	global_load_dwordx4 v[154:157], v213, s[38:39]
	s_add_u32 s38, s38, 0xe000
	s_addc_u32 s39, s39, 0
	global_load_dwordx4 v[158:161], v213, s[38:39]
	v_lshrrev_b32_e32 v14, 2, v12
	v_lshl_add_u64 v[0:1], s[0:1], 0, v[2:3]
	v_lshlrev_b32_e32 v199, 2, v13
	v_lshlrev_b32_e32 v17, 3, v12
	v_lshl_add_u64 v[168:169], v[0:1], 0, v[4:5]
	v_and_or_b32 v2, v14, 3, v199
	v_lshlrev_b32_e32 v3, 1, v12
	v_lshl_add_u64 v[184:185], v[0:1], 0, v[6:7]
	v_and_or_b32 v0, s22, 32, v252
	v_mul_u32_u24_e32 v2, 0x90, v2
	v_and_b32_e32 v35, 32, v3
	v_and_b32_e32 v3, 24, v17
	s_add_i32 s0, s6, s7
	v_or_b32_e32 v0, 0x200, v0
	v_lshlrev_b32_e32 v32, 3, v13
	v_add_u32_e32 v33, v15, v6
	v_add3_u32 v37, v15, v2, v3
	v_mul_u32_u24_e32 v39, 0x90, v16
	s_add_i32 s11, s0, 0xfffffe00
	v_sub_u32_e32 v0, v0, v199
	s_lshl_b32 s0, s29, 6
	v_mov_b32_e32 v251, 0
	v_mov_b32_e32 v248, v224
	v_and_b32_e32 v232, 63, v12
	v_ashrrev_i32_e32 v163, 31, v162
	s_waitcnt lgkmcnt(0)
	v_mov_b32_e32 v167, v166
	v_mov_b32_e32 v170, v166
	v_mov_b32_e32 v171, v166
	v_mov_b32_e32 v172, v166
	v_mov_b32_e32 v173, v166
	v_mov_b32_e32 v174, v166
	v_mov_b32_e32 v175, v166
	v_mov_b32_e32 v176, v166
	v_mov_b32_e32 v177, v166
	v_mov_b32_e32 v178, v166
	v_mov_b32_e32 v179, v166
	v_mov_b32_e32 v180, v166
	v_mov_b32_e32 v181, v166
	v_mov_b32_e32 v182, v166
	v_mov_b32_e32 v183, v166
	v_lshl_add_u64 v[186:187], v[168:169], 0, v[112:113]
	s_add_i32 s28, s29, -1
	v_subrev_u32_e32 v247, s0, v0
	v_mov_b32_e32 v16, v113
	v_mov_b32_e32 v17, v113
	v_mov_b32_e32 v18, v113
	v_mov_b32_e32 v19, v113
	v_mov_b32_e32 v20, v113
	v_mov_b32_e32 v21, v113
	v_mov_b32_e32 v22, v113
	v_mov_b32_e32 v23, v113
	v_mov_b32_e32 v24, v113
	v_mov_b32_e32 v25, v113
	v_mov_b32_e32 v26, v113
	v_mov_b32_e32 v27, v113
	v_mov_b32_e32 v28, v113
	v_mov_b32_e32 v29, v113
	v_mov_b32_e32 v30, v113
	v_mov_b32_e32 v31, v113
	v_mov_b32_e32 v0, v113
	v_mov_b32_e32 v1, v113
	v_mov_b32_e32 v2, v113
	v_mov_b32_e32 v3, v113
	v_mov_b32_e32 v4, v113
	v_mov_b32_e32 v6, v113
	v_mov_b32_e32 v8, v113
	v_mov_b32_e32 v9, v113
	v_mov_b32_e32 v10, v113
	v_mov_b32_e32 v12, v113
	v_mov_b32_e32 v13, v113
	v_mov_b32_e32 v14, v113
	v_mov_b32_e32 v15, v113
	v_mov_b32_e32 v233, 0xf149f2ca
	v_add_u32_e32 v245, v33, v39
	v_lshlrev_b32_e32 v188, 1, v34
	v_lshlrev_b32_e32 v190, 1, v36
	v_lshlrev_b32_e32 v192, 1, v38
	v_lshlrev_b32_e32 v194, 1, v40
	v_lshlrev_b32_e32 v196, 1, v42
	v_lshlrev_b32_e32 v112, 1, v32
	v_add_u32_e32 v250, v37, v35
	s_waitcnt vmcnt(12)
	ds_write_b128 v214, v[80:83]
	ds_write_b128 v214, v[84:87] offset:1152
	ds_write_b128 v214, v[88:91] offset:2304
	ds_write_b128 v214, v[92:95] offset:3456
.LBB0_264:
	s_waitcnt lgkmcnt(0)
	ds_read_b128 v[80:83], v215
	ds_read_b128 v[84:87], v215 offset:32
	ds_read_b128 v[88:91], v215 offset:64
	ds_read_b128 v[92:95], v215 offset:96
	s_cmp_lg_u32 s28, 7
	s_cselect_b64 s[4:5], -1, 0
	s_cmp_eq_u32 s28, 7
	s_waitcnt vmcnt(4)
	ds_write_b128 v245, v[96:99]
	ds_write_b128 v245, v[100:103] offset:1152
	ds_write_b128 v245, v[104:107] offset:2304
	ds_write_b128 v245, v[108:111] offset:3456
	ds_write_b128 v245, v[114:117] offset:4608
	ds_write_b128 v245, v[118:121] offset:5760
	ds_write_b128 v245, v[122:125] offset:6912
	ds_write_b128 v245, v[126:129] offset:8064
	s_cbranch_scc1 .LBB0_266
	s_add_i32 s0, s11, 64
	v_mad_i64_i32 v[32:33], s[0:1], s0, v238, v[184:185]
	v_mov_b32_e32 v189, v113
	v_lshl_add_u64 v[34:35], v[32:33], 0, v[188:189]
	v_add_co_u32_e32 v36, vcc, 0xe000, v34
	v_mov_b32_e32 v191, v113
	s_nop 0
	v_addc_co_u32_e32 v37, vcc, 0, v35, vcc
	global_load_dwordx4 v[96:99], v[34:35], off offset:2048
	global_load_dwordx4 v[100:103], v[36:37], off offset:2048
	v_add_co_u32_e32 v36, vcc, 0x1c000, v34
	v_mov_b32_e32 v193, v113
	s_nop 0
	v_addc_co_u32_e32 v37, vcc, 0, v35, vcc
	v_add_co_u32_e32 v34, vcc, 0x2a000, v34
	v_mov_b32_e32 v195, v113
	s_nop 0
	v_addc_co_u32_e32 v35, vcc, 0, v35, vcc
	global_load_dwordx4 v[104:107], v[36:37], off offset:2048
	global_load_dwordx4 v[108:111], v[34:35], off offset:2048
	v_lshl_add_u64 v[34:35], v[32:33], 0, v[190:191]
	v_lshl_add_u64 v[36:37], v[32:33], 0, v[192:193]
	global_load_dwordx4 v[114:117], v[34:35], off offset:2048
	global_load_dwordx4 v[118:121], v[36:37], off offset:2048
	v_lshl_add_u64 v[34:35], v[32:33], 0, v[194:195]
	v_mov_b32_e32 v197, v113
	v_lshl_add_u64 v[32:33], v[32:33], 0, v[196:197]
	global_load_dwordx4 v[122:125], v[34:35], off offset:2048
	global_load_dwordx4 v[126:129], v[32:33], off offset:2048
.LBB0_266:
	s_waitcnt lgkmcnt(8)
	v_mfma_f32_32x32x16_bf16 v[48:63], v[80:83], v[64:67], 0
	s_waitcnt lgkmcnt(0)
	ds_read_b64_tr_b16 v[142:143], v250
	ds_read_b64_tr_b16 v[144:145], v250 offset:1152
	ds_read_b64_tr_b16 v[132:133], v250 offset:1216
	ds_read_b64_tr_b16 v[130:131], v250 offset:64
	ds_read_b64_tr_b16 v[138:139], v250 offset:2304
	ds_read_b64_tr_b16 v[140:141], v250 offset:3456
	ds_read_b64_tr_b16 v[136:137], v250 offset:3520
	ds_read_b64_tr_b16 v[134:135], v250 offset:2368
	s_add_i32 s28, s28, 1
	s_cmp_lt_u32 s28, 4
	s_cselect_b64 s[6:7], -1, 0
	v_mfma_f32_32x32x16_bf16 v[48:63], v[84:87], v[68:71], v[48:63]
	v_mfma_f32_32x32x16_bf16 v[48:63], v[88:91], v[72:75], v[48:63]
	v_mfma_f32_32x32x16_bf16 v[48:63], v[92:95], v[76:79], v[48:63]
	s_andn2_b64 vcc, exec, s[4:5]
	s_cbranch_vccnz .Latt_A3_last
	s_waitcnt vmcnt(8)
	ds_write_b128 v214, v[146:149]
	ds_write_b128 v214, v[150:153] offset:1152
	ds_write_b128 v214, v[154:157] offset:2304
	ds_write_b128 v214, v[158:161] offset:3456
	s_add_i32 s38, s11, 64
	s_mul_i32 s38, s38, 0x1c00
	s_add_i32 s38, s38, 0x6000000
	s_add_u32 s38, s2, s38
	s_addc_u32 s39, s3, 0
	global_load_dwordx4 v[146:149], v213, s[38:39]
	s_add_u32 s38, s38, 0xe000
	s_addc_u32 s39, s39, 0
	global_load_dwordx4 v[150:153], v213, s[38:39]
	s_add_u32 s38, s38, 0xe000
	s_addc_u32 s39, s39, 0
	global_load_dwordx4 v[154:157], v213, s[38:39]
	s_add_u32 s38, s38, 0xe000
	s_addc_u32 s39, s39, 0
	global_load_dwordx4 v[158:161], v213, s[38:39]
.Latt_A3_done:
	s_cmp_gt_u32 s28, 3
	s_mov_b64 s[0:1], -1
	s_cbranch_scc1 .LBB0_268
	s_nop 10
	v_pk_add_f32 v[46:47], v[182:183], v[62:63]
	v_pk_add_f32 v[44:45], v[180:181], v[60:61]
	v_pk_add_f32 v[42:43], v[178:179], v[58:59]
	v_pk_add_f32 v[40:41], v[176:177], v[56:57]
	v_pk_add_f32 v[38:39], v[174:175], v[54:55]
	v_pk_add_f32 v[36:37], v[172:173], v[52:53]
	v_pk_add_f32 v[34:35], v[170:171], v[50:51]
	v_pk_add_f32 v[32:33], v[166:167], v[48:49]
	s_mov_b64 s[0:1], 0

.LBB0_270:
	s_nop 8
	v_max_f32_e32 v48, v33, v33
	v_max_f32_e32 v49, v32, v32
	v_max_f32_e32 v48, v49, v48
	v_max3_f32 v48, v48, v34, v35
	v_max3_f32 v48, v48, v36, v37
	v_max3_f32 v48, v48, v38, v39
	v_max3_f32 v48, v48, v40, v41
	v_xor_b32_e32 v49, 32, v236
	v_add_u32_e32 v50, 64, v237
	v_max3_f32 v48, v48, v42, v43
	v_cmp_lt_i32_e32 vcc, v49, v50
	v_max3_f32 v48, v48, v44, v45
	v_max3_f32 v48, v48, v46, v47
	v_cndmask_b32_e32 v49, v236, v49, vcc
	v_lshlrev_b32_e32 v189, 2, v49
	ds_bpermute_b32 v49, v189, v48
	s_waitcnt lgkmcnt(0)
	v_max3_f32 v191, v233, v48, v49
	v_sub_f32_e32 v48, v233, v191
	v_exp_f32_e32 v198, v48
	v_cmp_gt_f32_e32 vcc, v191, v233
	s_cbranch_vccz .LBB0_272
	v_pk_mul_f32 v[14:15], v[14:15], v[198:199] op_sel_hi:[1,0]
	v_pk_mul_f32 v[12:13], v[12:13], v[198:199] op_sel_hi:[1,0]
	v_pk_mul_f32 v[10:11], v[10:11], v[198:199] op_sel_hi:[1,0]
	v_pk_mul_f32 v[8:9], v[8:9], v[198:199] op_sel_hi:[1,0]
	v_pk_mul_f32 v[6:7], v[6:7], v[198:199] op_sel_hi:[1,0]
	v_pk_mul_f32 v[4:5], v[4:5], v[198:199] op_sel_hi:[1,0]
	v_pk_mul_f32 v[2:3], v[2:3], v[198:199] op_sel_hi:[1,0]
	v_pk_mul_f32 v[0:1], v[0:1], v[198:199] op_sel_hi:[1,0]
	v_pk_mul_f32 v[30:31], v[30:31], v[198:199] op_sel_hi:[1,0]
	v_pk_mul_f32 v[28:29], v[28:29], v[198:199] op_sel_hi:[1,0]
	v_pk_mul_f32 v[26:27], v[26:27], v[198:199] op_sel_hi:[1,0]
	v_pk_mul_f32 v[24:25], v[24:25], v[198:199] op_sel_hi:[1,0]
	v_pk_mul_f32 v[22:23], v[22:23], v[198:199] op_sel_hi:[1,0]
	v_pk_mul_f32 v[20:21], v[20:21], v[198:199] op_sel_hi:[1,0]
	v_pk_mul_f32 v[18:19], v[18:19], v[198:199] op_sel_hi:[1,0]
	v_pk_mul_f32 v[16:17], v[16:17], v[198:199] op_sel_hi:[1,0]
.LBB0_272:
	v_sub_f32_e32 v32, v32, v191
	v_exp_f32_e32 v193, v32
	v_sub_f32_e32 v32, v33, v191
	v_exp_f32_e32 v195, v32
	v_sub_f32_e32 v32, v34, v191
	v_exp_f32_e32 v197, v32
	v_sub_f32_e32 v32, v35, v191
	v_exp_f32_e32 v200, v32
	v_sub_f32_e32 v32, v36, v191
	v_exp_f32_e32 v201, v32
	v_sub_f32_e32 v32, v37, v191
	v_exp_f32_e32 v202, v32
	v_sub_f32_e32 v32, v38, v191
	v_exp_f32_e32 v203, v32
	v_sub_f32_e32 v32, v39, v191
	v_exp_f32_e32 v204, v32
	v_sub_f32_e32 v32, v40, v191
	v_exp_f32_e32 v205, v32
	v_sub_f32_e32 v32, v41, v191
	v_exp_f32_e32 v206, v32
	v_sub_f32_e32 v32, v42, v191
	v_exp_f32_e32 v207, v32
	v_sub_f32_e32 v32, v43, v191
	v_exp_f32_e32 v208, v32
	v_sub_f32_e32 v32, v44, v191
	v_exp_f32_e32 v209, v32
	v_sub_f32_e32 v32, v45, v191
	v_exp_f32_e32 v210, v32
	v_sub_f32_e32 v32, v46, v191
	v_exp_f32_e32 v211, v32
	v_sub_f32_e32 v32, v47, v191
	v_exp_f32_e32 v212, v32
	v_cvt_pk_bf16_f32 v32, v193, v195
	v_cvt_pk_bf16_f32 v33, v197, v200
	v_cvt_pk_bf16_f32 v34, v201, v202
	v_cvt_pk_bf16_f32 v35, v203, v204
	v_cvt_pk_bf16_f32 v36, v205, v206
	v_cvt_pk_bf16_f32 v37, v207, v208
	v_mfma_f32_32x32x16_bf16 v[16:31], v[142:145], v[32:35], v[16:31]
	v_cvt_pk_bf16_f32 v38, v209, v210
	v_cvt_pk_bf16_f32 v39, v211, v212
	v_mfma_f32_32x32x16_bf16 v[0:15], v[130:133], v[32:35], v[0:15]
	v_mfma_f32_32x32x16_bf16 v[16:31], v[138:141], v[36:39], v[16:31]
	v_mfma_f32_32x32x16_bf16 v[0:15], v[134:137], v[36:39], v[0:15]
.LBB0_274:
	ds_read_b128 v[80:83], v215
	ds_read_b128 v[84:87], v215 offset:32
	ds_read_b128 v[88:91], v215 offset:64
	ds_read_b128 v[92:95], v215 offset:96
	s_waitcnt lgkmcnt(0)
	v_mfma_f32_32x32x16_bf16 v[48:63], v[80:83], v[64:67], 0
	ds_read_b64_tr_b16 v[142:143], v250 offset:4608
	ds_read_b64_tr_b16 v[144:145], v250 offset:5760
	ds_read_b64_tr_b16 v[138:139], v250 offset:6912
	ds_read_b64_tr_b16 v[140:141], v250 offset:8064
	ds_read_b64_tr_b16 v[134:135], v250 offset:4672
	ds_read_b64_tr_b16 v[136:137], v250 offset:5824
	ds_read_b64_tr_b16 v[130:131], v250 offset:6976
	ds_read_b64_tr_b16 v[132:133], v250 offset:8128
	s_mov_b64 s[0:1], -1
	v_mfma_f32_32x32x16_bf16 v[48:63], v[84:87], v[68:71], v[48:63]
	v_mfma_f32_32x32x16_bf16 v[48:63], v[88:91], v[72:75], v[48:63]
	v_mfma_f32_32x32x16_bf16 v[48:63], v[92:95], v[76:79], v[48:63]
	s_andn2_b64 vcc, exec, s[4:5]
	s_cbranch_vccnz .Latt_B3_done
	s_waitcnt vmcnt(0)
	ds_write_b128 v214, v[146:149]
	ds_write_b128 v214, v[150:153] offset:1152
	ds_write_b128 v214, v[154:157] offset:2304
	ds_write_b128 v214, v[158:161] offset:3456
	s_add_i32 s38, s11, 0x60
	s_mul_i32 s38, s38, 0x1c00
	s_add_i32 s38, s38, 0x6000000
	s_add_u32 s38, s2, s38
	s_addc_u32 s39, s3, 0
	global_load_dwordx4 v[146:149], v213, s[38:39]
	s_add_u32 s38, s38, 0xe000
	s_addc_u32 s39, s39, 0
	global_load_dwordx4 v[150:153], v213, s[38:39]
	s_add_u32 s38, s38, 0xe000
	s_addc_u32 s39, s39, 0
	global_load_dwordx4 v[154:157], v213, s[38:39]
	s_add_u32 s38, s38, 0xe000
	s_addc_u32 s39, s39, 0
	global_load_dwordx4 v[158:161], v213, s[38:39]
.Latt_B3_done:
	s_andn2_b64 vcc, exec, s[6:7]
	s_cbranch_vccnz .LBB0_276
	s_nop 10
	v_pk_add_f32 v[46:47], v[182:183], v[62:63]
	v_pk_add_f32 v[44:45], v[180:181], v[60:61]
	v_pk_add_f32 v[42:43], v[178:179], v[58:59]
	v_pk_add_f32 v[40:41], v[176:177], v[56:57]
	v_pk_add_f32 v[38:39], v[174:175], v[54:55]
	v_pk_add_f32 v[36:37], v[172:173], v[52:53]
	v_pk_add_f32 v[34:35], v[170:171], v[50:51]
	v_pk_add_f32 v[32:33], v[166:167], v[48:49]
	s_mov_b64 s[0:1], 0
.LBB0_276:
	s_andn2_b64 vcc, exec, s[0:1]
	s_cbranch_vccnz .LBB0_278
	v_subrev_u32_e32 v32, 32, v247
	v_min_i32_e32 v33, 0x100, v32
	v_lshl_add_u32 v40, v33, 2, v246
	v_min_i32_e32 v33, 0x101, v32
	v_lshl_add_u32 v41, v33, 2, v246
	v_min_i32_e32 v33, 0x102, v32
	v_lshl_add_u32 v42, v33, 2, v246
	v_min_i32_e32 v33, 0x103, v32
	v_lshl_add_u32 v43, v33, 2, v246
	v_min_i32_e32 v33, 0x108, v32
	v_lshl_add_u32 v44, v33, 2, v246
	v_min_i32_e32 v33, 0x109, v32
	v_lshl_add_u32 v45, v33, 2, v246
	v_min_i32_e32 v33, 0x10a, v32
	v_lshl_add_u32 v46, v33, 2, v246
	v_min_i32_e32 v33, 0x10b, v32
	v_lshl_add_u32 v47, v33, 2, v246
	v_min_i32_e32 v33, 0x110, v32
	v_min_i32_e32 v34, 0x111, v32
	v_min_i32_e32 v35, 0x112, v32
	v_min_i32_e32 v36, 0x113, v32
	v_min_i32_e32 v37, 0x118, v32
	v_min_i32_e32 v38, 0x119, v32
	v_min_i32_e32 v39, 0x11a, v32
	v_min_i32_e32 v32, 0x11b, v32
	v_lshl_add_u32 v33, v33, 2, v246
	v_lshl_add_u32 v34, v34, 2, v246
	v_lshl_add_u32 v35, v35, 2, v246
	v_lshl_add_u32 v36, v36, 2, v246
	v_lshl_add_u32 v37, v37, 2, v246
	v_lshl_add_u32 v38, v38, 2, v246
	v_lshl_add_u32 v39, v39, 2, v246
	v_lshl_add_u32 v216, v32, 2, v246
	ds_read_b32 v32, v33 offset:188
	ds_read_b32 v33, v34 offset:184
	ds_read_b32 v34, v35 offset:180
	ds_read_b32 v35, v36 offset:176
	ds_read_b32 v36, v37 offset:156
	ds_read_b32 v37, v38 offset:152
	ds_read_b32 v38, v39 offset:148
	ds_read_b32 v39, v216 offset:144
	ds_read_b32 v216, v40 offset:252
	ds_read_b32 v217, v41 offset:248
	ds_read_b32 v218, v42 offset:244
	ds_read_b32 v219, v43 offset:240
	ds_read_b32 v220, v44 offset:220
	ds_read_b32 v221, v45 offset:216
	ds_read_b32 v222, v46 offset:212
	ds_read_b32 v223, v47 offset:208
	s_waitcnt lgkmcnt(8)
	v_pk_add_f32 v[46:47], v[62:63], v[38:39]
	v_pk_add_f32 v[44:45], v[60:61], v[36:37]
	v_pk_add_f32 v[42:43], v[58:59], v[34:35]
	v_pk_add_f32 v[40:41], v[56:57], v[32:33]
	s_waitcnt lgkmcnt(0)
	v_pk_add_f32 v[38:39], v[54:55], v[222:223]
	v_pk_add_f32 v[36:37], v[52:53], v[220:221]
	v_pk_add_f32 v[34:35], v[50:51], v[218:219]
	v_pk_add_f32 v[32:33], v[48:49], v[216:217]

.LBB0_280:
	v_sub_f32_e32 v32, v32, v233
	v_exp_f32_e32 v32, v32
	v_sub_f32_e32 v33, v33, v233
	v_exp_f32_e32 v33, v33
	v_sub_f32_e32 v34, v34, v233
	v_exp_f32_e32 v34, v34
	v_sub_f32_e32 v35, v35, v233
	v_sub_f32_e32 v36, v36, v233
	v_sub_f32_e32 v37, v37, v233
	v_sub_f32_e32 v38, v38, v233
	v_sub_f32_e32 v39, v39, v233
	v_exp_f32_e32 v35, v35
	v_exp_f32_e32 v36, v36
	v_exp_f32_e32 v37, v37
	v_exp_f32_e32 v38, v38
	v_exp_f32_e32 v39, v39
	v_add_f32_e32 v50, 0, v32
	v_add_f32_e32 v50, v33, v50
	v_add_f32_e32 v49, 0, v193
	v_add_f32_e32 v50, v34, v50
	v_add_f32_e32 v49, v195, v49
	v_add_f32_e32 v50, v35, v50
	v_cvt_pk_bf16_f32 v32, v32, v33
	v_cvt_pk_bf16_f32 v33, v34, v35
	v_cvt_pk_bf16_f32 v34, v36, v37
	v_cvt_pk_bf16_f32 v35, v38, v39
	v_add_f32_e32 v49, v197, v49
	v_add_f32_e32 v49, v200, v49
	v_mfma_f32_32x32x16_bf16 v[16:31], v[142:145], v[32:35], v[16:31]
	v_add_f32_e32 v49, v201, v49
	v_sub_f32_e32 v40, v40, v233
	v_sub_f32_e32 v41, v41, v233
	v_sub_f32_e32 v42, v42, v233
	v_sub_f32_e32 v43, v43, v233
	v_sub_f32_e32 v44, v44, v233
	v_sub_f32_e32 v45, v45, v233
	v_mfma_f32_32x32x16_bf16 v[0:15], v[134:137], v[32:35], v[0:15]
	v_sub_f32_e32 v46, v46, v233
	v_sub_f32_e32 v47, v47, v233
	v_add_f32_e32 v49, v202, v49
	v_add_f32_e32 v50, v36, v50
	v_exp_f32_e32 v40, v40
	v_exp_f32_e32 v41, v41
	v_exp_f32_e32 v42, v42
	v_exp_f32_e32 v43, v43
	v_exp_f32_e32 v44, v44
	v_exp_f32_e32 v45, v45
	v_exp_f32_e32 v46, v46
	v_exp_f32_e32 v47, v47
	v_add_f32_e32 v49, v203, v49
	v_add_f32_e32 v50, v37, v50
	v_add_f32_e32 v49, v204, v49
	v_add_f32_e32 v50, v38, v50
	v_add_f32_e32 v49, v205, v49
	v_add_f32_e32 v50, v39, v50
	v_add_f32_e32 v49, v206, v49
	v_add_f32_e32 v50, v40, v50
	v_cvt_pk_bf16_f32 v36, v40, v41
	v_cvt_pk_bf16_f32 v37, v42, v43
	v_cvt_pk_bf16_f32 v38, v44, v45
	v_cvt_pk_bf16_f32 v39, v46, v47
	v_add_f32_e32 v49, v207, v49
	v_add_f32_e32 v50, v41, v50
	v_mfma_f32_32x32x16_bf16 v[16:31], v[138:141], v[36:39], v[16:31]
	v_add_f32_e32 v49, v208, v49
	v_add_f32_e32 v50, v42, v50
	v_add_f32_e32 v49, v209, v49
	v_add_f32_e32 v50, v43, v50
	v_add_f32_e32 v49, v210, v49
	v_add_f32_e32 v50, v44, v50
	v_add_f32_e32 v49, v211, v49
	v_mfma_f32_32x32x16_bf16 v[0:15], v[130:133], v[36:39], v[0:15]
	v_add_f32_e32 v50, v45, v50
	v_add_f32_e32 v49, v212, v49
	v_add_f32_e32 v50, v46, v50
	v_fmac_f32_e32 v49, v251, v198
	v_add_f32_e32 v251, v47, v50
	s_add_i32 s11, s11, 64
	v_fmac_f32_e32 v251, v49, v48
	v_subrev_u32_e32 v247, 64, v247
	s_cmp_gt_u32 s28, 7
	s_cbranch_scc1 .LBB0_282
	s_branch .LBB0_264
.Latt_A3_last:
	s_waitcnt vmcnt(0)
	ds_write_b128 v214, v[146:149]
	ds_write_b128 v214, v[150:153] offset:1152
	ds_write_b128 v214, v[154:157] offset:2304
	ds_write_b128 v214, v[158:161] offset:3456
	s_branch .Latt_A3_done

.LBB0_284:
	s_or_b64 exec, exec, s[0:1]
	s_waitcnt lgkmcnt(0)
	s_barrier
	s_load_dwordx2 s[0:1], s[8:9], 0x68
	s_lshl_b32 s4, s21, 2
	v_mov_b32_e32 v225, 0x358637bd
	v_mov_b32_e32 v226, 0x260
	v_lshlrev_b32_e32 v112, 2, v199
	s_waitcnt lgkmcnt(0)
	s_add_u32 s0, s0, s4
	s_addc_u32 s1, s1, 0
	s_lshl_b32 s4, s10, 2
	s_add_i32 s4, s20, s4
	v_lshl_add_u32 v18, v252, 2, s4
	ds_read2st64_b32 v[16:17], v18 offset1:1
	v_mov_b32_e32 v224, v248
	v_add_u32_e32 v227, -1, v236
	v_add_u32_e32 v228, -2, v236
	v_add_u32_e32 v229, -4, v236
	s_waitcnt lgkmcnt(0)
	v_add_f32_e32 v16, 0, v16
	v_add_f32_e32 v19, v16, v17
	ds_read2st64_b32 v[16:17], v18 offset0:2 offset1:3
	v_add_u32_e32 v230, -8, v236
	v_add_u32_e32 v231, -16, v236
	v_subrev_u32_e32 v232, 32, v236
	v_bfrev_b32_e32 v233, 0.5
	s_waitcnt lgkmcnt(0)
	v_add_f32_e32 v16, v19, v16
	v_add_f32_e32 v19, v16, v17
	ds_read2st64_b32 v[16:17], v18 offset0:4 offset1:5
	v_mov_b32_e32 v234, 0x1400
	v_mov_b32_e32 v235, 0x1000
	v_mov_b32_e32 v239, 0xf800000
	v_mov_b32_e32 v240, 0xf400000
	s_waitcnt lgkmcnt(0)
	v_add_f32_e32 v16, v19, v16
	v_add_f32_e32 v19, v16, v17
	ds_read2st64_b32 v[16:17], v18 offset0:6 offset1:7
	s_waitcnt lgkmcnt(0)
	v_add_f32_e32 v16, v19, v16
	v_add_f32_e32 v16, v16, v17
	v_lshl_add_u64 v[18:19], v[164:165], 2, s[0:1]
	v_fmamk_f32 v16, v16, 0x3b000000, v225
	s_mov_b32 s0, 0xf800000
	v_cmp_gt_f32_e32 vcc, s0, v16
	v_mul_f32_e32 v17, 0x4f800000, v16
	v_lshl_add_u64 v[18:19], v[18:19], 0, v[112:113]
	v_cndmask_b32_e32 v16, v16, v17, vcc
	v_sqrt_f32_e32 v17, v16
	v_lshlrev_b32_e32 v112, 1, v199
	v_add_u32_e32 v36, -1, v17
	v_fma_f32 v37, -v36, v17, v16
	v_cmp_ge_f32_e64 s[38:39], 0, v37
	v_add_u32_e32 v37, 1, v17
	s_nop 0
	v_cndmask_b32_e64 v36, v17, v36, s[38:39]
	v_fma_f32 v17, -v37, v17, v16
	v_cmp_lt_f32_e64 s[38:39], 0, v17
	s_nop 1
	v_cndmask_b32_e64 v17, v36, v37, s[38:39]
	v_mul_f32_e32 v36, 0x37800000, v17
	v_cndmask_b32_e32 v17, v17, v36, vcc
	v_cmp_class_f32_e32 vcc, v16, v226
	s_nop 1
	v_cndmask_b32_e32 v16, v17, v16, vcc
	v_div_scale_f32 v17, s[0:1], v16, v16, 1.0
	v_rcp_f32_e32 v36, v17
	s_mov_b64 s[0:1], 0x1e00000
	v_fma_f32 v37, -v17, v36, 1.0
	v_fmac_f32_e32 v36, v37, v36
	v_div_scale_f32 v37, vcc, 1.0, v16, 1.0
	v_mul_f32_e32 v38, v37, v36
	v_fma_f32 v39, -v17, v38, v37
	v_fmac_f32_e32 v38, v39, v36
	v_fma_f32 v17, -v17, v38, v37
	v_div_fmas_f32 v17, v17, v36, v38
	global_load_dwordx4 v[38:41], v[18:19], off
	global_load_dwordx4 v[96:99], v[18:19], off offset:32
	global_load_dwordx4 v[100:103], v[18:19], off offset:64
	global_load_dwordx4 v[104:107], v[18:19], off offset:96
	global_load_dwordx4 v[108:111], v[18:19], off offset:128
	global_load_dwordx4 v[114:117], v[18:19], off offset:160
	global_load_dwordx4 v[118:121], v[18:19], off offset:192
	global_load_dwordx4 v[122:125], v[18:19], off offset:224
	v_lshlrev_b64 v[36:37], 11, v[162:163]
	v_div_fixup_f32 v16, v17, v16, 1.0
	v_lshl_add_u64 v[36:37], s[2:3], 0, v[36:37]
	v_lshl_add_u64 v[36:37], v[164:165], 1, v[36:37]
	v_pk_mul_f32 v[34:35], v[34:35], v[16:17] op_sel_hi:[1,0]
	v_pk_mul_f32 v[32:33], v[32:33], v[16:17] op_sel_hi:[1,0]
	v_lshl_add_u64 v[36:37], v[36:37], 0, v[112:113]
	v_pk_mul_f32 v[20:21], v[20:21], v[16:17] op_sel_hi:[1,0]
	v_pk_mul_f32 v[22:23], v[22:23], v[16:17] op_sel_hi:[1,0]
	v_pk_mul_f32 v[24:25], v[24:25], v[16:17] op_sel_hi:[1,0]
	v_pk_mul_f32 v[0:1], v[0:1], v[16:17] op_sel_hi:[1,0]
	v_pk_mul_f32 v[2:3], v[2:3], v[16:17] op_sel_hi:[1,0]
	v_pk_mul_f32 v[4:5], v[4:5], v[16:17] op_sel_hi:[1,0]
	s_waitcnt vmcnt(7)
	v_pk_mul_f32 v[34:35], v[38:39], v[34:35]
	v_pk_mul_f32 v[32:33], v[40:41], v[32:33]
	v_cvt_pk_bf16_f32 v34, v34, v35
	v_cvt_pk_bf16_f32 v35, v32, v33
	v_lshl_add_u64 v[32:33], v[36:37], 0, s[0:1]
	s_mov_b32 s0, 0x1e00000
	v_add_co_u32_e32 v36, vcc, s0, v36
	s_mov_b64 s[0:1], 0
	s_nop 0
	v_addc_co_u32_e32 v37, vcc, 0, v37, vcc
	global_store_dwordx2 v[36:37], v[34:35], off
	s_waitcnt vmcnt(7)
	v_pk_mul_f32 v[20:21], v[96:97], v[20:21]
	v_pk_mul_f32 v[22:23], v[98:99], v[22:23]
	v_cvt_pk_bf16_f32 v20, v20, v21
	v_cvt_pk_bf16_f32 v21, v22, v23
	global_store_dwordx2 v[32:33], v[20:21], off offset:16
	s_waitcnt vmcnt(7)
	v_pk_mul_f32 v[20:21], v[24:25], v[100:101]
	v_pk_mul_f32 v[24:25], v[26:27], v[16:17] op_sel_hi:[1,0]
	v_cvt_pk_bf16_f32 v20, v20, v21
	v_pk_mul_f32 v[22:23], v[24:25], v[102:103]
	v_pk_mul_f32 v[24:25], v[28:29], v[16:17] op_sel_hi:[1,0]
	v_cvt_pk_bf16_f32 v21, v22, v23
	global_store_dwordx2 v[32:33], v[20:21], off offset:32
	s_waitcnt vmcnt(7)
	v_pk_mul_f32 v[20:21], v[24:25], v[104:105]
	v_pk_mul_f32 v[24:25], v[30:31], v[16:17] op_sel_hi:[1,0]
	v_cvt_pk_bf16_f32 v20, v20, v21
	v_pk_mul_f32 v[22:23], v[24:25], v[106:107]
	s_nop 0
	v_cvt_pk_bf16_f32 v21, v22, v23
	global_store_dwordx2 v[32:33], v[20:21], off offset:48
	s_waitcnt vmcnt(7)
	v_pk_mul_f32 v[0:1], v[0:1], v[108:109]
	v_pk_mul_f32 v[2:3], v[2:3], v[110:111]
	v_cvt_pk_bf16_f32 v0, v0, v1
	v_cvt_pk_bf16_f32 v1, v2, v3
	global_store_dwordx2 v[32:33], v[0:1], off offset:64
	s_waitcnt vmcnt(7)
	v_pk_mul_f32 v[0:1], v[4:5], v[114:115]
	v_pk_mul_f32 v[4:5], v[6:7], v[16:17] op_sel_hi:[1,0]
	v_cvt_pk_bf16_f32 v0, v0, v1
	v_pk_mul_f32 v[2:3], v[4:5], v[116:117]
	v_pk_mul_f32 v[4:5], v[8:9], v[16:17] op_sel_hi:[1,0]
	v_cvt_pk_bf16_f32 v1, v2, v3
	global_store_dwordx2 v[32:33], v[0:1], off offset:80
	s_waitcnt vmcnt(7)
	v_pk_mul_f32 v[0:1], v[4:5], v[118:119]
	v_pk_mul_f32 v[4:5], v[10:11], v[16:17] op_sel_hi:[1,0]
	v_cvt_pk_bf16_f32 v0, v0, v1
	v_pk_mul_f32 v[2:3], v[4:5], v[120:121]
	v_pk_mul_f32 v[4:5], v[12:13], v[16:17] op_sel_hi:[1,0]
	v_cvt_pk_bf16_f32 v1, v2, v3
	global_store_dwordx2 v[32:33], v[0:1], off offset:96
	s_waitcnt vmcnt(7)
	v_pk_mul_f32 v[0:1], v[4:5], v[122:123]
	v_pk_mul_f32 v[4:5], v[14:15], v[16:17] op_sel_hi:[1,0]
	v_cvt_pk_bf16_f32 v0, v0, v1
	v_pk_mul_f32 v[2:3], v[4:5], v[124:125]
	s_nop 0
	v_cvt_pk_bf16_f32 v1, v2, v3
	global_store_dwordx2 v[32:33], v[0:1], off offset:112
	s_barrier

.LBB0_310:
	s_barrier
	s_and_b64 s[0:1], exec, s[48:49]
	s_cselect_b32 s13, 1, s13
	s_cmp_ge_i32 s12, s14
	s_cbranch_scc1 .LBB0_380
